# v54 with the leader's local release issued before its invalidate
# speedup vs baseline: 1.0070x; 1.0070x over previous
; __device__ __forceinline__ unsigned xb_ld(unsigned* p)              { return __hip_atomic_load(p, __ATOMIC_RELAXED, __HIP_MEMORY_SCOPE_AGENT); }
; __device__ __forceinline__ unsigned xb_add(unsigned* p, unsigned v) { return __hip_atomic_fetch_add(p, v, __ATOMIC_RELAXED, __HIP_MEMORY_SCOPE_AGENT); }
; #define XB_SPIN(cond, bar) do { unsigned _sp = 0; while (cond) { __builtin_amdgcn_s_sleep(1); \
;     if ((++_sp & 255u) == 0u) { if (xb_ld(&(bar)[XB_TMO])) break; if (_sp > XB_SPIN_CAP) { atomicAdd(&(bar)[XB_TMO], 1u); break; } } } } while (0)
; __device__ __forceinline__ void xcd_barrier(const XcdBarrier& b) {
;     ...
;         const unsigned old = xb_add(&bar[XB_XSUB(b.x)], 1u);
;         const unsigned gen = old / nloc;
;         if (old + 1u == (gen + 1u) * nloc) {
;             __builtin_amdgcn_fence(__ATOMIC_RELEASE, "agent");
;             asm volatile("s_waitcnt vmcnt(0)" ::: "memory");
;             const unsigned og = xb_add(&bar[XB_TOP], 1u);
;             const unsigned tg = og / nx;
;             if (og + 1u == (tg + 1u) * nx) xb_add(&bar[XB_TOPGEN], 1u);
;             else XB_SPIN(xb_ld(&bar[XB_TOPGEN]) == tg, bar);
;             __builtin_amdgcn_fence(__ATOMIC_ACQUIRE, "agent");
;             xb_add(&bar[XB_XGEN(b.x)], 1u);
;             asm volatile("s_waitcnt vmcnt(0)" ::: "memory");
.LBB0_14:
	s_or_b64 exec, exec, s[8:9]
	v_mov_b32_e32 v0, 0x2000
	s_waitcnt vmcnt(0)
	global_atomic_add v0, v183, s[6:7] offset:1024
	buffer_inv sc1
